# adds: the two pre-barrier waits of each GEMM load segment merged into one s_waitcnt vmcnt(8) lgkmcnt(0)
# speedup vs baseline: 1.0183x; 1.0004x over previous
; #define PG8_STAGE(bufoff, gbase, voff) do { _Pragma("unroll") for (int _i = 0; _i < 2; ++_i) \
;         __builtin_amdgcn_global_load_lds((const unsigned*)((const char*)(gbase) + (voff)[_i]), (PG8_LAS unsigned*)(lds + (bufoff) + ldsw + _i * 8192), 16, 0, 0); } while (0)
; #define PG8_LDA(dst, b, h) do { _Pragma("unroll") for (int m = 0; m < 4; ++m) _Pragma("unroll") for (int k = 0; k < 2; ++k) dst[m][k] = *(const PG8_LAS bf16x8*)(lds + PG8_SA(b, h) + aoff + m * 2048 + k * 1024); } while (0)
; #define PG8_LDB(dst, b, h) do { _Pragma("unroll") for (int n = 0; n < 2; ++n) _Pragma("unroll") for (int k = 0; k < 2; ++k) dst[n][k] = *(const PG8_LAS bf16x8*)(lds + PG8_SB(b, h) + boff + n * 2048 + k * 1024); } while (0)
; #define PG8_MMA(ai, bj, At, Bt) do { __builtin_amdgcn_s_setprio(1); _Pragma("unroll") for (int m = 0; m < 4; ++m) _Pragma("unroll") for (int n = 0; n < 2; ++n) _Pragma("unroll") for (int k = 0; k < 2; ++k) \
;         acc[ai][bj][m][n] = __builtin_amdgcn_mfma_f32_16x16x32_bf16(Bt[n][k], At[m][k], acc[ai][bj][m][n], 0, 0, 0); __builtin_amdgcn_s_setprio(0); } while (0)
; #define PG8_WAIT_V(n) asm volatile("s_waitcnt vmcnt(" #n ")" ::: "memory")
; #define PG8_WAIT_L(n) asm volatile("s_waitcnt lgkmcnt(" #n ")" ::: "memory")
; #define PG8_BAR __builtin_amdgcn_s_barrier()
; #define PG8_SCHED __builtin_amdgcn_sched_barrier(0)
; template <class Epi, class Sched, bool ALIGN_EPI = false, bool SP2 = false>
; __device__ __forceinline__ void gemm_phase(PG8_LAS unsigned char* lds, const Gemm g, const Sched& S, const Epi& E) {
;     ...
;         for (int t = 0; t < nt; t += 2) {
;             const bool last = (t == nt - 2);
;             const char* a1 = cA + (size_t)(t + 1) * kstepB;
;             const char* a2 = last ? nA : cA + (size_t)(t + 2) * kstepB; const char* b2 = last ? nB : cB + (size_t)(t + 2) * kstepB;
;             const char* a3 = a2 + kstepB; const char* b3 = b2 + kstepB;
;             if (last && has_next) S.a_ready(nxt);
;             if constexpr (SP2) {
;             PG8_LDB(B0, 0, 0); PG8_LDB(B1, 0, 1); PG8_SCHED; PG8_LDA(At, 0, 0); PG8_STAGE(PG8_SA(1, 1), a1 + hstepB, voffA);
;             PG8_WAIT_V(8); PG8_WAIT_L(0); PG8_BAR; PG8_MMA(0, 0, At, B0); PG8_MMA(0, 1, At, B1); PG8_BAR; PG8_SCHED;
;             PG8_LDA(At, 0, 1); PG8_STAGE(PG8_SB(0, 0), b2, voffB); PG8_STAGE(PG8_SB(0, 1), b2 + hstepB, voffB); PG8_STAGE(PG8_SA(0, 0), a2, voffA);
.LBB0_193:
	s_add_i32 s84, s38, 2
	s_add_u32 s39, s36, 0x4000
	s_addc_u32 s40, s37, 0
	s_cmp_eq_u32 s31, s38
	s_cselect_b32 s42, s8, s39
	s_cselect_b32 s43, s9, s40
	s_cselect_b32 s40, s62, s78
	s_cselect_b32 s41, s63, s82
	s_add_u32 s38, s42, 0x8000
	s_addc_u32 s39, s43, 0
	s_add_i32 s90, 0, 0x10000
	s_add_i32 s64, 0, 0x14000
	v_add_u32_e32 v140, s90, v174
	v_add_u32_e32 v161, s64, v174
	ds_read_b128 v[128:131], v140
	ds_read_b128 v[132:135], v140 offset:1024
	ds_read_b128 v[136:139], v140 offset:2048
	ds_read_b128 v[140:143], v140 offset:3072
	ds_read_b128 v[144:147], v161
	ds_read_b128 v[148:151], v161 offset:1024
	ds_read_b128 v[178:181], v161 offset:2048
	ds_read_b128 v[182:185], v161 offset:3072
	v_lshl_add_u64 v[172:173], s[36:37], 0, v[168:169]
	s_add_i32 m0, s21, 0xc000
	ds_read_b128 v[186:189], v177
	ds_read_b128 v[190:193], v177 offset:1024
	ds_read_b128 v[194:197], v177 offset:2048
	ds_read_b128 v[198:201], v177 offset:3072
	ds_read_b128 v[202:205], v177 offset:4096
	ds_read_b128 v[206:209], v177 offset:5120
	ds_read_b128 v[210:213], v177 offset:6144
	ds_read_b128 v[214:217], v177 offset:7168
	global_load_lds_dwordx4 v[172:173], off
	v_lshl_add_u64 v[172:173], s[36:37], 0, v[170:171]
	s_add_i32 m0, s21, 0xe000
	s_nop 0
	global_load_lds_dwordx4 v[172:173], off
	s_setprio 1
	s_waitcnt vmcnt(8) lgkmcnt(0)
	s_barrier
	v_mfma_f32_16x16x32_bf16 v[124:127], v[128:131], v[186:189], v[124:127]
	v_mfma_f32_16x16x32_bf16 v[124:127], v[132:135], v[190:193], v[124:127]
	v_mfma_f32_16x16x32_bf16 v[120:123], v[136:139], v[186:189], v[120:123]
	v_mfma_f32_16x16x32_bf16 v[120:123], v[140:143], v[190:193], v[120:123]
	v_mfma_f32_16x16x32_bf16 v[108:111], v[128:131], v[194:197], v[108:111]
	v_mfma_f32_16x16x32_bf16 v[108:111], v[132:135], v[198:201], v[108:111]
	v_mfma_f32_16x16x32_bf16 v[104:107], v[136:139], v[194:197], v[104:107]
	v_mfma_f32_16x16x32_bf16 v[104:107], v[140:143], v[198:201], v[104:107]
	v_mfma_f32_16x16x32_bf16 v[92:95], v[128:131], v[202:205], v[92:95]
	v_mfma_f32_16x16x32_bf16 v[92:95], v[132:135], v[206:209], v[92:95]
	v_mfma_f32_16x16x32_bf16 v[88:91], v[136:139], v[202:205], v[88:91]
	v_mfma_f32_16x16x32_bf16 v[88:91], v[140:143], v[206:209], v[88:91]
	v_mfma_f32_16x16x32_bf16 v[76:79], v[128:131], v[210:213], v[76:79]
	v_mfma_f32_16x16x32_bf16 v[76:79], v[132:135], v[214:217], v[76:79]
	v_mfma_f32_16x16x32_bf16 v[72:75], v[136:139], v[210:213], v[72:75]
	v_mfma_f32_16x16x32_bf16 v[72:75], v[140:143], v[214:217], v[72:75]
	v_mfma_f32_16x16x32_bf16 v[116:119], v[144:147], v[186:189], v[116:119]
	v_mfma_f32_16x16x32_bf16 v[116:119], v[148:151], v[190:193], v[116:119]
	v_mfma_f32_16x16x32_bf16 v[112:115], v[178:181], v[186:189], v[112:115]
	v_mfma_f32_16x16x32_bf16 v[112:115], v[182:185], v[190:193], v[112:115]
	v_mfma_f32_16x16x32_bf16 v[100:103], v[144:147], v[194:197], v[100:103]
	v_mfma_f32_16x16x32_bf16 v[100:103], v[148:151], v[198:201], v[100:103]
	v_mfma_f32_16x16x32_bf16 v[96:99], v[178:181], v[194:197], v[96:99]
	v_mfma_f32_16x16x32_bf16 v[96:99], v[182:185], v[198:201], v[96:99]
	v_mfma_f32_16x16x32_bf16 v[84:87], v[144:147], v[202:205], v[84:87]
	v_mfma_f32_16x16x32_bf16 v[84:87], v[148:151], v[206:209], v[84:87]
	v_mfma_f32_16x16x32_bf16 v[80:83], v[178:181], v[202:205], v[80:83]
	v_mfma_f32_16x16x32_bf16 v[80:83], v[182:185], v[206:209], v[80:83]
	v_mfma_f32_16x16x32_bf16 v[68:71], v[144:147], v[210:213], v[68:71]
	v_mfma_f32_16x16x32_bf16 v[68:71], v[148:151], v[214:217], v[68:71]
	v_mfma_f32_16x16x32_bf16 v[64:67], v[178:181], v[210:213], v[64:67]
	v_mfma_f32_16x16x32_bf16 v[64:67], v[182:185], v[214:217], v[64:67]
	s_barrier
	s_setprio 0
	s_add_i32 s65, s90, s20
	v_lshl_add_u64 v[172:173], s[40:41], 0, v[156:157]
	s_mov_b32 m0, s65
	ds_read_b128 v[186:189], v177 offset:16384
	ds_read_b128 v[190:193], v177 offset:17408
	ds_read_b128 v[194:197], v177 offset:18432
	ds_read_b128 v[198:201], v177 offset:19456
	ds_read_b128 v[202:205], v177 offset:20480
	ds_read_b128 v[206:209], v177 offset:21504
	ds_read_b128 v[210:213], v177 offset:22528
	ds_read_b128 v[214:217], v177 offset:23552
	global_load_lds_dwordx4 v[172:173], off
	s_add_i32 m0, s65, 0x2000
	s_add_u32 vcc_lo, s40, 0x4000
	v_lshl_add_u64 v[172:173], s[40:41], 0, v[152:153]
	s_addc_u32 vcc_hi, s41, 0
	s_add_i32 s64, s64, s20
	global_load_lds_dwordx4 v[172:173], off
	v_lshl_add_u64 v[172:173], vcc, 0, v[156:157]
	s_mov_b32 m0, s64
	s_nop 0
	global_load_lds_dwordx4 v[172:173], off
	v_lshl_add_u64 v[172:173], vcc, 0, v[152:153]
	s_add_i32 m0, s64, 0x2000
	s_nop 0
	global_load_lds_dwordx4 v[172:173], off
	v_lshl_add_u64 v[172:173], s[42:43], 0, v[158:159]
	s_mov_b32 m0, s21
	s_nop 0
	global_load_lds_dwordx4 v[172:173], off
	v_lshl_add_u64 v[172:173], s[42:43], 0, v[154:155]
	s_mov_b32 m0, s22
	s_nop 0
	global_load_lds_dwordx4 v[172:173], off
	s_setprio 1
	s_waitcnt vmcnt(8) lgkmcnt(0)
	s_barrier
; #define PG8_STAGE(bufoff, gbase, voff) do { _Pragma("unroll") for (int _i = 0; _i < 2; ++_i) \
;         __builtin_amdgcn_global_load_lds((const unsigned*)((const char*)(gbase) + (voff)[_i]), (PG8_LAS unsigned*)(lds + (bufoff) + ldsw + _i * 8192), 16, 0, 0); } while (0)
; #define PG8_LDA(dst, b, h) do { _Pragma("unroll") for (int m = 0; m < 4; ++m) _Pragma("unroll") for (int k = 0; k < 2; ++k) dst[m][k] = *(const PG8_LAS bf16x8*)(lds + PG8_SA(b, h) + aoff + m * 2048 + k * 1024); } while (0)
; #define PG8_LDB(dst, b, h) do { _Pragma("unroll") for (int n = 0; n < 2; ++n) _Pragma("unroll") for (int k = 0; k < 2; ++k) dst[n][k] = *(const PG8_LAS bf16x8*)(lds + PG8_SB(b, h) + boff + n * 2048 + k * 1024); } while (0)
; #define PG8_MMA(ai, bj, At, Bt) do { __builtin_amdgcn_s_setprio(1); _Pragma("unroll") for (int m = 0; m < 4; ++m) _Pragma("unroll") for (int n = 0; n < 2; ++n) _Pragma("unroll") for (int k = 0; k < 2; ++k) \
;         acc[ai][bj][m][n] = __builtin_amdgcn_mfma_f32_16x16x32_bf16(Bt[n][k], At[m][k], acc[ai][bj][m][n], 0, 0, 0); __builtin_amdgcn_s_setprio(0); } while (0)
; #define PG8_WAIT_V(n) asm volatile("s_waitcnt vmcnt(" #n ")" ::: "memory")
; #define PG8_WAIT_L(n) asm volatile("s_waitcnt lgkmcnt(" #n ")" ::: "memory")
; #define PG8_BAR __builtin_amdgcn_s_barrier()
; #define PG8_SCHED __builtin_amdgcn_sched_barrier(0)
; template <class Epi, class Sched, bool ALIGN_EPI = false, bool SP2 = false>
; __device__ __forceinline__ void gemm_phase(PG8_LAS unsigned char* lds, const Gemm g, const Sched& S, const Epi& E) {
;     ...
;             PG8_WAIT_V(8); PG8_WAIT_L(0); PG8_BAR; PG8_MMA(1, 0, At, B0); PG8_MMA(1, 1, At, B1); PG8_BAR; PG8_SCHED;
;             PG8_LDB(B0, 1, 0); PG8_LDB(B1, 1, 1); PG8_SCHED; PG8_LDA(At, 1, 0); PG8_STAGE(PG8_SA(0, 1), a2 + hstepB, voffA);
;             PG8_WAIT_V(8); PG8_WAIT_L(0); PG8_BAR; PG8_MMA(0, 0, At, B0); PG8_MMA(0, 1, At, B1); PG8_BAR; PG8_SCHED;
	v_mfma_f32_16x16x32_bf16 v[60:63], v[128:131], v[186:189], v[60:63]
	v_mfma_f32_16x16x32_bf16 v[60:63], v[132:135], v[190:193], v[60:63]
	v_mfma_f32_16x16x32_bf16 v[56:59], v[136:139], v[186:189], v[56:59]
	v_mfma_f32_16x16x32_bf16 v[56:59], v[140:143], v[190:193], v[56:59]
	v_mfma_f32_16x16x32_bf16 v[44:47], v[128:131], v[194:197], v[44:47]
	v_mfma_f32_16x16x32_bf16 v[44:47], v[132:135], v[198:201], v[44:47]
	v_mfma_f32_16x16x32_bf16 v[40:43], v[136:139], v[194:197], v[40:43]
	v_mfma_f32_16x16x32_bf16 v[40:43], v[140:143], v[198:201], v[40:43]
	v_mfma_f32_16x16x32_bf16 v[28:31], v[128:131], v[202:205], v[28:31]
	v_mfma_f32_16x16x32_bf16 v[28:31], v[132:135], v[206:209], v[28:31]
	v_mfma_f32_16x16x32_bf16 v[24:27], v[136:139], v[202:205], v[24:27]
	v_mfma_f32_16x16x32_bf16 v[24:27], v[140:143], v[206:209], v[24:27]
	v_mfma_f32_16x16x32_bf16 v[12:15], v[128:131], v[210:213], v[12:15]
	v_mfma_f32_16x16x32_bf16 v[12:15], v[132:135], v[214:217], v[12:15]
	v_mfma_f32_16x16x32_bf16 v[8:11], v[136:139], v[210:213], v[8:11]
	v_mfma_f32_16x16x32_bf16 v[8:11], v[140:143], v[214:217], v[8:11]
	v_mfma_f32_16x16x32_bf16 v[52:55], v[144:147], v[186:189], v[52:55]
	v_mfma_f32_16x16x32_bf16 v[52:55], v[148:151], v[190:193], v[52:55]
	v_mfma_f32_16x16x32_bf16 v[48:51], v[178:181], v[186:189], v[48:51]
	v_mfma_f32_16x16x32_bf16 v[48:51], v[182:185], v[190:193], v[48:51]
	v_mfma_f32_16x16x32_bf16 v[36:39], v[144:147], v[194:197], v[36:39]
	v_mfma_f32_16x16x32_bf16 v[36:39], v[148:151], v[198:201], v[36:39]
	v_mfma_f32_16x16x32_bf16 v[32:35], v[178:181], v[194:197], v[32:35]
	v_mfma_f32_16x16x32_bf16 v[32:35], v[182:185], v[198:201], v[32:35]
	v_mfma_f32_16x16x32_bf16 v[20:23], v[144:147], v[202:205], v[20:23]
	v_mfma_f32_16x16x32_bf16 v[20:23], v[148:151], v[206:209], v[20:23]
	v_mfma_f32_16x16x32_bf16 v[16:19], v[178:181], v[202:205], v[16:19]
	v_mfma_f32_16x16x32_bf16 v[16:19], v[182:185], v[206:209], v[16:19]
	v_mfma_f32_16x16x32_bf16 v[4:7], v[144:147], v[210:213], v[4:7]
	v_mfma_f32_16x16x32_bf16 v[4:7], v[148:151], v[214:217], v[4:7]
	v_mfma_f32_16x16x32_bf16 v[0:3], v[178:181], v[210:213], v[0:3]
	v_mfma_f32_16x16x32_bf16 v[0:3], v[182:185], v[214:217], v[0:3]
	s_barrier
	s_setprio 0
	s_add_i32 s64, 0, 0x18000
	s_add_i32 s65, 0, 0x1c000
	v_add_u32_e32 v140, s64, v174
	v_add_u32_e32 v161, s65, v174
	ds_read_b128 v[128:131], v140
	ds_read_b128 v[132:135], v140 offset:1024
	ds_read_b128 v[136:139], v140 offset:2048
	ds_read_b128 v[140:143], v140 offset:3072
	ds_read_b128 v[144:147], v161
	ds_read_b128 v[148:151], v161 offset:1024
	ds_read_b128 v[178:181], v161 offset:2048
	ds_read_b128 v[182:185], v161 offset:3072
	s_add_u32 s42, s42, 0x4000
	s_addc_u32 s43, s43, 0
	s_mov_b32 m0, s23
	v_lshl_add_u64 v[172:173], s[42:43], 0, v[158:159]
	ds_read_b128 v[186:189], v177 offset:32768
	ds_read_b128 v[190:193], v177 offset:33792
	ds_read_b128 v[194:197], v177 offset:34816
	ds_read_b128 v[198:201], v177 offset:35840
	ds_read_b128 v[202:205], v177 offset:36864
	ds_read_b128 v[206:209], v177 offset:37888
	ds_read_b128 v[210:213], v177 offset:38912
	ds_read_b128 v[214:217], v177 offset:39936
	global_load_lds_dwordx4 v[172:173], off
	v_lshl_add_u64 v[172:173], s[42:43], 0, v[154:155]
	s_mov_b32 m0, s24
	s_nop 0
	global_load_lds_dwordx4 v[172:173], off
	s_setprio 1
	s_waitcnt vmcnt(8) lgkmcnt(0)
	s_barrier
	v_mfma_f32_16x16x32_bf16 v[124:127], v[128:131], v[186:189], v[124:127]
	v_mfma_f32_16x16x32_bf16 v[124:127], v[132:135], v[190:193], v[124:127]
	v_mfma_f32_16x16x32_bf16 v[120:123], v[136:139], v[186:189], v[120:123]
	v_mfma_f32_16x16x32_bf16 v[120:123], v[140:143], v[190:193], v[120:123]
	v_mfma_f32_16x16x32_bf16 v[108:111], v[128:131], v[194:197], v[108:111]
	v_mfma_f32_16x16x32_bf16 v[108:111], v[132:135], v[198:201], v[108:111]
	v_mfma_f32_16x16x32_bf16 v[104:107], v[136:139], v[194:197], v[104:107]
	v_mfma_f32_16x16x32_bf16 v[104:107], v[140:143], v[198:201], v[104:107]
	v_mfma_f32_16x16x32_bf16 v[92:95], v[128:131], v[202:205], v[92:95]
	v_mfma_f32_16x16x32_bf16 v[92:95], v[132:135], v[206:209], v[92:95]
	v_mfma_f32_16x16x32_bf16 v[88:91], v[136:139], v[202:205], v[88:91]
	v_mfma_f32_16x16x32_bf16 v[88:91], v[140:143], v[206:209], v[88:91]
	v_mfma_f32_16x16x32_bf16 v[76:79], v[128:131], v[210:213], v[76:79]
	v_mfma_f32_16x16x32_bf16 v[76:79], v[132:135], v[214:217], v[76:79]
	v_mfma_f32_16x16x32_bf16 v[72:75], v[136:139], v[210:213], v[72:75]
	v_mfma_f32_16x16x32_bf16 v[72:75], v[140:143], v[214:217], v[72:75]
	v_mfma_f32_16x16x32_bf16 v[116:119], v[144:147], v[186:189], v[116:119]
	v_mfma_f32_16x16x32_bf16 v[116:119], v[148:151], v[190:193], v[116:119]
	v_mfma_f32_16x16x32_bf16 v[112:115], v[178:181], v[186:189], v[112:115]
	v_mfma_f32_16x16x32_bf16 v[112:115], v[182:185], v[190:193], v[112:115]
	v_mfma_f32_16x16x32_bf16 v[100:103], v[144:147], v[194:197], v[100:103]
	v_mfma_f32_16x16x32_bf16 v[100:103], v[148:151], v[198:201], v[100:103]
	v_mfma_f32_16x16x32_bf16 v[96:99], v[178:181], v[194:197], v[96:99]
	v_mfma_f32_16x16x32_bf16 v[96:99], v[182:185], v[198:201], v[96:99]
	v_mfma_f32_16x16x32_bf16 v[84:87], v[144:147], v[202:205], v[84:87]
	v_mfma_f32_16x16x32_bf16 v[84:87], v[148:151], v[206:209], v[84:87]
	v_mfma_f32_16x16x32_bf16 v[80:83], v[178:181], v[202:205], v[80:83]
	v_mfma_f32_16x16x32_bf16 v[80:83], v[182:185], v[206:209], v[80:83]
	v_mfma_f32_16x16x32_bf16 v[68:71], v[144:147], v[210:213], v[68:71]
	v_mfma_f32_16x16x32_bf16 v[68:71], v[148:151], v[214:217], v[68:71]
	v_mfma_f32_16x16x32_bf16 v[64:67], v[178:181], v[210:213], v[64:67]
	v_mfma_f32_16x16x32_bf16 v[64:67], v[182:185], v[214:217], v[64:67]
	s_barrier
; #define PG8_STAGE(bufoff, gbase, voff) do { _Pragma("unroll") for (int _i = 0; _i < 2; ++_i) \
;         __builtin_amdgcn_global_load_lds((const unsigned*)((const char*)(gbase) + (voff)[_i]), (PG8_LAS unsigned*)(lds + (bufoff) + ldsw + _i * 8192), 16, 0, 0); } while (0)
; #define PG8_LDA(dst, b, h) do { _Pragma("unroll") for (int m = 0; m < 4; ++m) _Pragma("unroll") for (int k = 0; k < 2; ++k) dst[m][k] = *(const PG8_LAS bf16x8*)(lds + PG8_SA(b, h) + aoff + m * 2048 + k * 1024); } while (0)
; #define PG8_MMA(ai, bj, At, Bt) do { __builtin_amdgcn_s_setprio(1); _Pragma("unroll") for (int m = 0; m < 4; ++m) _Pragma("unroll") for (int n = 0; n < 2; ++n) _Pragma("unroll") for (int k = 0; k < 2; ++k) \
;         acc[ai][bj][m][n] = __builtin_amdgcn_mfma_f32_16x16x32_bf16(Bt[n][k], At[m][k], acc[ai][bj][m][n], 0, 0, 0); __builtin_amdgcn_s_setprio(0); } while (0)
; #define PG8_WAIT_V(n) asm volatile("s_waitcnt vmcnt(" #n ")" ::: "memory")
; #define PG8_WAIT_L(n) asm volatile("s_waitcnt lgkmcnt(" #n ")" ::: "memory")
; #define PG8_BAR __builtin_amdgcn_s_barrier()
; #define PG8_SCHED __builtin_amdgcn_sched_barrier(0)
; template <class Epi, class Sched, bool ALIGN_EPI = false, bool SP2 = false>
; __device__ __forceinline__ void gemm_phase(PG8_LAS unsigned char* lds, const Gemm g, const Sched& S, const Epi& E) {
;     ...
;             PG8_LDA(At, 1, 1); PG8_STAGE(PG8_SB(1, 0), b3, voffB); PG8_STAGE(PG8_SB(1, 1), b3 + hstepB, voffB); PG8_STAGE(PG8_SA(1, 0), a3, voffA);
;             PG8_WAIT_V(8); PG8_WAIT_L(0); PG8_BAR; PG8_MMA(1, 0, At, B0); PG8_MMA(1, 1, At, B1); PG8_BAR; PG8_SCHED;
;     ...
;         if constexpr (ALIGN_EPI) { if (wr == 0) PG8_BAR; }
	s_setprio 0
	s_add_u32 s42, s40, 0x8000
	s_addc_u32 s43, s41, 0
	s_add_i32 s64, s64, s20
	v_lshl_add_u64 v[172:173], s[42:43], 0, v[156:157]
	s_mov_b32 m0, s64
	ds_read_b128 v[186:189], v177 offset:49152
	ds_read_b128 v[190:193], v177 offset:50176
	ds_read_b128 v[194:197], v177 offset:51200
	ds_read_b128 v[198:201], v177 offset:52224
	ds_read_b128 v[202:205], v177 offset:53248
	ds_read_b128 v[206:209], v177 offset:54272
	ds_read_b128 v[210:213], v177 offset:55296
	ds_read_b128 v[214:217], v177 offset:56320
	global_load_lds_dwordx4 v[172:173], off
	s_add_i32 m0, s64, 0x2000
	s_add_u32 s40, s40, 0xc000
	v_lshl_add_u64 v[172:173], s[42:43], 0, v[152:153]
	s_addc_u32 s41, s41, 0
	s_add_i32 s42, s65, s20
	global_load_lds_dwordx4 v[172:173], off
	v_lshl_add_u64 v[172:173], s[40:41], 0, v[156:157]
	s_mov_b32 m0, s42
	s_nop 0
	global_load_lds_dwordx4 v[172:173], off
	v_lshl_add_u64 v[172:173], s[40:41], 0, v[152:153]
	s_add_i32 m0, s42, 0x2000
	s_nop 0
	global_load_lds_dwordx4 v[172:173], off
	v_lshl_add_u64 v[172:173], s[38:39], 0, v[158:159]
	s_mov_b32 m0, s29
	s_nop 0
	global_load_lds_dwordx4 v[172:173], off
	v_lshl_add_u64 v[172:173], s[38:39], 0, v[154:155]
	s_mov_b32 m0, s30
	s_nop 0
	global_load_lds_dwordx4 v[172:173], off
	s_setprio 1
	s_waitcnt vmcnt(8) lgkmcnt(0)
	s_barrier
	v_mfma_f32_16x16x32_bf16 v[60:63], v[128:131], v[186:189], v[60:63]
	v_mfma_f32_16x16x32_bf16 v[60:63], v[132:135], v[190:193], v[60:63]
	v_mfma_f32_16x16x32_bf16 v[56:59], v[136:139], v[186:189], v[56:59]
	v_mfma_f32_16x16x32_bf16 v[56:59], v[140:143], v[190:193], v[56:59]
	v_mfma_f32_16x16x32_bf16 v[44:47], v[128:131], v[194:197], v[44:47]
	v_mfma_f32_16x16x32_bf16 v[44:47], v[132:135], v[198:201], v[44:47]
	v_mfma_f32_16x16x32_bf16 v[40:43], v[136:139], v[194:197], v[40:43]
	v_mfma_f32_16x16x32_bf16 v[40:43], v[140:143], v[198:201], v[40:43]
	v_mfma_f32_16x16x32_bf16 v[28:31], v[128:131], v[202:205], v[28:31]
	v_mfma_f32_16x16x32_bf16 v[28:31], v[132:135], v[206:209], v[28:31]
	v_mfma_f32_16x16x32_bf16 v[24:27], v[136:139], v[202:205], v[24:27]
	v_mfma_f32_16x16x32_bf16 v[24:27], v[140:143], v[206:209], v[24:27]
	v_mfma_f32_16x16x32_bf16 v[12:15], v[128:131], v[210:213], v[12:15]
	v_mfma_f32_16x16x32_bf16 v[12:15], v[132:135], v[214:217], v[12:15]
	v_mfma_f32_16x16x32_bf16 v[8:11], v[136:139], v[210:213], v[8:11]
	v_mfma_f32_16x16x32_bf16 v[8:11], v[140:143], v[214:217], v[8:11]
	v_mfma_f32_16x16x32_bf16 v[52:55], v[144:147], v[186:189], v[52:55]
	v_mfma_f32_16x16x32_bf16 v[52:55], v[148:151], v[190:193], v[52:55]
	v_mfma_f32_16x16x32_bf16 v[48:51], v[178:181], v[186:189], v[48:51]
	v_mfma_f32_16x16x32_bf16 v[48:51], v[182:185], v[190:193], v[48:51]
	v_mfma_f32_16x16x32_bf16 v[36:39], v[144:147], v[194:197], v[36:39]
	v_mfma_f32_16x16x32_bf16 v[36:39], v[148:151], v[198:201], v[36:39]
	v_mfma_f32_16x16x32_bf16 v[32:35], v[178:181], v[194:197], v[32:35]
	v_mfma_f32_16x16x32_bf16 v[32:35], v[182:185], v[198:201], v[32:35]
	v_mfma_f32_16x16x32_bf16 v[20:23], v[144:147], v[202:205], v[20:23]
	v_mfma_f32_16x16x32_bf16 v[20:23], v[148:151], v[206:209], v[20:23]
	v_mfma_f32_16x16x32_bf16 v[16:19], v[178:181], v[202:205], v[16:19]
	v_mfma_f32_16x16x32_bf16 v[16:19], v[182:185], v[206:209], v[16:19]
	v_mfma_f32_16x16x32_bf16 v[4:7], v[144:147], v[210:213], v[4:7]
	v_mfma_f32_16x16x32_bf16 v[4:7], v[148:151], v[214:217], v[4:7]
	v_mfma_f32_16x16x32_bf16 v[0:3], v[178:181], v[210:213], v[0:3]
	v_mfma_f32_16x16x32_bf16 v[0:3], v[182:185], v[214:217], v[0:3]
	s_barrier
	s_setprio 0
	s_add_u32 s36, s36, 0x10000
	s_addc_u32 s37, s37, 0
	s_add_u32 s78, s78, 0x10000
	s_addc_u32 s82, s82, 0
	s_cmp_ge_u32 s84, s26
	s_mov_b32 s38, s84
	s_cbranch_scc0 .LBB0_193
	s_and_b64 vcc, exec, s[60:61]
	s_cbranch_vccz .LBB0_196
	s_barrier

; #define PG8_STAGE(bufoff, gbase, voff) do { _Pragma("unroll") for (int _i = 0; _i < 2; ++_i) \
;         __builtin_amdgcn_global_load_lds((const unsigned*)((const char*)(gbase) + (voff)[_i]), (PG8_LAS unsigned*)(lds + (bufoff) + ldsw + _i * 8192), 16, 0, 0); } while (0)
; #define PG8_LDA(dst, b, h) do { _Pragma("unroll") for (int m = 0; m < 4; ++m) _Pragma("unroll") for (int k = 0; k < 2; ++k) dst[m][k] = *(const PG8_LAS bf16x8*)(lds + PG8_SA(b, h) + aoff + m * 2048 + k * 1024); } while (0)
; #define PG8_LDB(dst, b, h) do { _Pragma("unroll") for (int n = 0; n < 2; ++n) _Pragma("unroll") for (int k = 0; k < 2; ++k) dst[n][k] = *(const PG8_LAS bf16x8*)(lds + PG8_SB(b, h) + boff + n * 2048 + k * 1024); } while (0)
; #define PG8_MMA(ai, bj, At, Bt) do { __builtin_amdgcn_s_setprio(1); _Pragma("unroll") for (int m = 0; m < 4; ++m) _Pragma("unroll") for (int n = 0; n < 2; ++n) _Pragma("unroll") for (int k = 0; k < 2; ++k) \
;         acc[ai][bj][m][n] = __builtin_amdgcn_mfma_f32_16x16x32_bf16(Bt[n][k], At[m][k], acc[ai][bj][m][n], 0, 0, 0); __builtin_amdgcn_s_setprio(0); } while (0)
; #define PG8_WAIT_V(n) asm volatile("s_waitcnt vmcnt(" #n ")" ::: "memory")
; #define PG8_WAIT_L(n) asm volatile("s_waitcnt lgkmcnt(" #n ")" ::: "memory")
; template <class Epi, class Sched, bool ALIGN_EPI = false, bool SP2 = false>
; __device__ __forceinline__ void gemm_phase(PG8_LAS unsigned char* lds, const Gemm g, const Sched& S, const Epi& E) {
;     ...
;             const bool last = (t == nt - 2);
;             const char* a1 = cA + (size_t)(t + 1) * kstepB;
;             const char* a2 = last ? nA : cA + (size_t)(t + 2) * kstepB; const char* b2 = last ? nB : cB + (size_t)(t + 2) * kstepB;
;             const char* a3 = a2 + kstepB; const char* b3 = b2 + kstepB;
;             if (last && has_next) S.a_ready(nxt);
;             if constexpr (SP2) {
;             PG8_LDB(B0, 0, 0); PG8_LDB(B1, 0, 1); PG8_SCHED; PG8_LDA(At, 0, 0); PG8_STAGE(PG8_SA(1, 1), a1 + hstepB, voffA);
;             PG8_WAIT_V(8); PG8_WAIT_L(0); PG8_BAR; PG8_MMA(0, 0, At, B0); PG8_MMA(0, 1, At, B1); PG8_BAR; PG8_SCHED;
;             PG8_LDA(At, 0, 1); PG8_STAGE(PG8_SB(0, 0), b2, voffB); PG8_STAGE(PG8_SB(0, 1), b2 + hstepB, voffB); PG8_STAGE(PG8_SA(0, 0), a2, voffA);
;             PG8_WAIT_V(8); PG8_WAIT_L(0); PG8_BAR; PG8_MMA(1, 0, At, B0); PG8_MMA(1, 1, At, B1); PG8_BAR; PG8_SCHED;
.LBB0_232:
	s_add_u32 s31, s36, 0x4000
	s_addc_u32 s38, s37, 0
	s_cmp_eq_u32 s30, 28
	s_cselect_b32 s42, s26, s31
	s_cselect_b32 s43, s13, s38
	s_cselect_b32 s40, s27, s28
	s_cselect_b32 s41, s11, s29
	s_add_u32 s38, s42, 0x8000
	s_addc_u32 s39, s43, 0
	s_add_i32 s31, 0, 0x10000
	s_add_i32 s60, 0, 0x14000
	v_add_u32_e32 v152, s31, v169
	v_add_u32_e32 v175, s60, v169
	ds_read_b128 v[128:131], v152
	ds_read_b128 v[132:135], v152 offset:1024
	ds_read_b128 v[148:151], v152 offset:2048
	ds_read_b128 v[152:155], v152 offset:3072
	ds_read_b128 v[156:159], v175
	ds_read_b128 v[160:163], v175 offset:1024
	ds_read_b128 v[164:167], v175 offset:2048
	ds_read_b128 v[176:179], v175 offset:3072
	v_lshl_add_u64 v[212:213], s[36:37], 0, v[144:145]
	s_add_i32 m0, s17, 0xc000
	ds_read_b128 v[180:183], v174
	ds_read_b128 v[184:187], v174 offset:1024
	ds_read_b128 v[188:191], v174 offset:2048
	ds_read_b128 v[192:195], v174 offset:3072
	ds_read_b128 v[196:199], v174 offset:4096
	ds_read_b128 v[200:203], v174 offset:5120
	ds_read_b128 v[204:207], v174 offset:6144
	ds_read_b128 v[208:211], v174 offset:7168
	global_load_lds_dwordx4 v[212:213], off
	v_lshl_add_u64 v[212:213], s[36:37], 0, v[146:147]
	s_add_i32 m0, s17, 0xe000
	s_nop 0
	global_load_lds_dwordx4 v[212:213], off
	s_setprio 1
	s_waitcnt vmcnt(8) lgkmcnt(0)
	s_barrier
	v_mfma_f32_16x16x32_bf16 v[124:127], v[128:131], v[180:183], v[124:127]
	v_mfma_f32_16x16x32_bf16 v[124:127], v[132:135], v[184:187], v[124:127]
	v_mfma_f32_16x16x32_bf16 v[120:123], v[148:151], v[180:183], v[120:123]
	v_mfma_f32_16x16x32_bf16 v[120:123], v[152:155], v[184:187], v[120:123]
	v_mfma_f32_16x16x32_bf16 v[108:111], v[128:131], v[188:191], v[108:111]
	v_mfma_f32_16x16x32_bf16 v[108:111], v[132:135], v[192:195], v[108:111]
	v_mfma_f32_16x16x32_bf16 v[104:107], v[148:151], v[188:191], v[104:107]
	v_mfma_f32_16x16x32_bf16 v[104:107], v[152:155], v[192:195], v[104:107]
	v_mfma_f32_16x16x32_bf16 v[92:95], v[128:131], v[196:199], v[92:95]
	v_mfma_f32_16x16x32_bf16 v[92:95], v[132:135], v[200:203], v[92:95]
	v_mfma_f32_16x16x32_bf16 v[88:91], v[148:151], v[196:199], v[88:91]
	v_mfma_f32_16x16x32_bf16 v[88:91], v[152:155], v[200:203], v[88:91]
	v_mfma_f32_16x16x32_bf16 v[76:79], v[128:131], v[204:207], v[76:79]
	v_mfma_f32_16x16x32_bf16 v[76:79], v[132:135], v[208:211], v[76:79]
	v_mfma_f32_16x16x32_bf16 v[72:75], v[148:151], v[204:207], v[72:75]
	v_mfma_f32_16x16x32_bf16 v[72:75], v[152:155], v[208:211], v[72:75]
	v_mfma_f32_16x16x32_bf16 v[116:119], v[156:159], v[180:183], v[116:119]
	v_mfma_f32_16x16x32_bf16 v[116:119], v[160:163], v[184:187], v[116:119]
	v_mfma_f32_16x16x32_bf16 v[112:115], v[164:167], v[180:183], v[112:115]
	v_mfma_f32_16x16x32_bf16 v[112:115], v[176:179], v[184:187], v[112:115]
	v_mfma_f32_16x16x32_bf16 v[100:103], v[156:159], v[188:191], v[100:103]
	v_mfma_f32_16x16x32_bf16 v[100:103], v[160:163], v[192:195], v[100:103]
	v_mfma_f32_16x16x32_bf16 v[96:99], v[164:167], v[188:191], v[96:99]
	v_mfma_f32_16x16x32_bf16 v[96:99], v[176:179], v[192:195], v[96:99]
	v_mfma_f32_16x16x32_bf16 v[84:87], v[156:159], v[196:199], v[84:87]
	v_mfma_f32_16x16x32_bf16 v[84:87], v[160:163], v[200:203], v[84:87]
	v_mfma_f32_16x16x32_bf16 v[80:83], v[164:167], v[196:199], v[80:83]
	v_mfma_f32_16x16x32_bf16 v[80:83], v[176:179], v[200:203], v[80:83]
	v_mfma_f32_16x16x32_bf16 v[68:71], v[156:159], v[204:207], v[68:71]
	v_mfma_f32_16x16x32_bf16 v[68:71], v[160:163], v[208:211], v[68:71]
	v_mfma_f32_16x16x32_bf16 v[64:67], v[164:167], v[204:207], v[64:67]
	v_mfma_f32_16x16x32_bf16 v[64:67], v[176:179], v[208:211], v[64:67]
	s_barrier
	s_setprio 0
	s_add_i32 s31, s31, s14
	v_lshl_add_u64 v[212:213], s[40:41], 0, v[220:221]
	s_mov_b32 m0, s31
	ds_read_b128 v[180:183], v174 offset:16384
	ds_read_b128 v[184:187], v174 offset:17408
	ds_read_b128 v[188:191], v174 offset:18432
	ds_read_b128 v[192:195], v174 offset:19456
	ds_read_b128 v[196:199], v174 offset:20480
	ds_read_b128 v[200:203], v174 offset:21504
	ds_read_b128 v[204:207], v174 offset:22528
	ds_read_b128 v[208:211], v174 offset:23552
	global_load_lds_dwordx4 v[212:213], off
	s_add_i32 m0, s31, 0x2000
	s_add_u32 s44, s40, 0x4000
	v_lshl_add_u64 v[212:213], s[40:41], 0, v[136:137]
	s_addc_u32 s45, s41, 0
	s_add_i32 s31, s60, s14
	global_load_lds_dwordx4 v[212:213], off
	v_lshl_add_u64 v[212:213], s[44:45], 0, v[220:221]
	s_mov_b32 m0, s31
	s_nop 0
	global_load_lds_dwordx4 v[212:213], off
	v_lshl_add_u64 v[212:213], s[44:45], 0, v[136:137]
	s_add_i32 m0, s31, 0x2000
	s_nop 0
	global_load_lds_dwordx4 v[212:213], off
	v_lshl_add_u64 v[212:213], s[42:43], 0, v[140:141]
	s_mov_b32 m0, s17
	s_nop 0
	global_load_lds_dwordx4 v[212:213], off
	v_lshl_add_u64 v[212:213], s[42:43], 0, v[138:139]
	s_mov_b32 m0, s18
	s_nop 0
	global_load_lds_dwordx4 v[212:213], off
	s_setprio 1
	s_waitcnt vmcnt(8) lgkmcnt(0)
	s_barrier
; #define PG8_STAGE(bufoff, gbase, voff) do { _Pragma("unroll") for (int _i = 0; _i < 2; ++_i) \
;         __builtin_amdgcn_global_load_lds((const unsigned*)((const char*)(gbase) + (voff)[_i]), (PG8_LAS unsigned*)(lds + (bufoff) + ldsw + _i * 8192), 16, 0, 0); } while (0)
; #define PG8_LDA(dst, b, h) do { _Pragma("unroll") for (int m = 0; m < 4; ++m) _Pragma("unroll") for (int k = 0; k < 2; ++k) dst[m][k] = *(const PG8_LAS bf16x8*)(lds + PG8_SA(b, h) + aoff + m * 2048 + k * 1024); } while (0)
; #define PG8_LDB(dst, b, h) do { _Pragma("unroll") for (int n = 0; n < 2; ++n) _Pragma("unroll") for (int k = 0; k < 2; ++k) dst[n][k] = *(const PG8_LAS bf16x8*)(lds + PG8_SB(b, h) + boff + n * 2048 + k * 1024); } while (0)
; #define PG8_MMA(ai, bj, At, Bt) do { __builtin_amdgcn_s_setprio(1); _Pragma("unroll") for (int m = 0; m < 4; ++m) _Pragma("unroll") for (int n = 0; n < 2; ++n) _Pragma("unroll") for (int k = 0; k < 2; ++k) \
;         acc[ai][bj][m][n] = __builtin_amdgcn_mfma_f32_16x16x32_bf16(Bt[n][k], At[m][k], acc[ai][bj][m][n], 0, 0, 0); __builtin_amdgcn_s_setprio(0); } while (0)
; #define PG8_WAIT_V(n) asm volatile("s_waitcnt vmcnt(" #n ")" ::: "memory")
; #define PG8_WAIT_L(n) asm volatile("s_waitcnt lgkmcnt(" #n ")" ::: "memory")
; #define PG8_BAR __builtin_amdgcn_s_barrier()
; #define PG8_SCHED __builtin_amdgcn_sched_barrier(0)
; template <class Epi, class Sched, bool ALIGN_EPI = false, bool SP2 = false>
; __device__ __forceinline__ void gemm_phase(PG8_LAS unsigned char* lds, const Gemm g, const Sched& S, const Epi& E) {
;     ...
;             PG8_WAIT_V(8); PG8_WAIT_L(0); PG8_BAR; PG8_MMA(1, 0, At, B0); PG8_MMA(1, 1, At, B1); PG8_BAR; PG8_SCHED;
;             PG8_LDB(B0, 1, 0); PG8_LDB(B1, 1, 1); PG8_SCHED; PG8_LDA(At, 1, 0); PG8_STAGE(PG8_SA(0, 1), a2 + hstepB, voffA);
;             PG8_WAIT_V(8); PG8_WAIT_L(0); PG8_BAR; PG8_MMA(0, 0, At, B0); PG8_MMA(0, 1, At, B1); PG8_BAR; PG8_SCHED;
	v_mfma_f32_16x16x32_bf16 v[60:63], v[128:131], v[180:183], v[60:63]
	v_mfma_f32_16x16x32_bf16 v[60:63], v[132:135], v[184:187], v[60:63]
	v_mfma_f32_16x16x32_bf16 v[56:59], v[148:151], v[180:183], v[56:59]
	v_mfma_f32_16x16x32_bf16 v[56:59], v[152:155], v[184:187], v[56:59]
	v_mfma_f32_16x16x32_bf16 v[48:51], v[128:131], v[188:191], v[48:51]
	v_mfma_f32_16x16x32_bf16 v[48:51], v[132:135], v[192:195], v[48:51]
	v_mfma_f32_16x16x32_bf16 v[40:43], v[148:151], v[188:191], v[40:43]
	v_mfma_f32_16x16x32_bf16 v[40:43], v[152:155], v[192:195], v[40:43]
	v_mfma_f32_16x16x32_bf16 v[32:35], v[128:131], v[196:199], v[32:35]
	v_mfma_f32_16x16x32_bf16 v[32:35], v[132:135], v[200:203], v[32:35]
	v_mfma_f32_16x16x32_bf16 v[24:27], v[148:151], v[196:199], v[24:27]
	v_mfma_f32_16x16x32_bf16 v[24:27], v[152:155], v[200:203], v[24:27]
	v_mfma_f32_16x16x32_bf16 v[16:19], v[128:131], v[204:207], v[16:19]
	v_mfma_f32_16x16x32_bf16 v[16:19], v[132:135], v[208:211], v[16:19]
	v_mfma_f32_16x16x32_bf16 v[8:11], v[148:151], v[204:207], v[8:11]
	v_mfma_f32_16x16x32_bf16 v[8:11], v[152:155], v[208:211], v[8:11]
	v_mfma_f32_16x16x32_bf16 v[52:55], v[156:159], v[180:183], v[52:55]
	v_mfma_f32_16x16x32_bf16 v[52:55], v[160:163], v[184:187], v[52:55]
	v_mfma_f32_16x16x32_bf16 v[44:47], v[164:167], v[180:183], v[44:47]
	v_mfma_f32_16x16x32_bf16 v[44:47], v[176:179], v[184:187], v[44:47]
	v_mfma_f32_16x16x32_bf16 v[36:39], v[156:159], v[188:191], v[36:39]
	v_mfma_f32_16x16x32_bf16 v[36:39], v[160:163], v[192:195], v[36:39]
	v_mfma_f32_16x16x32_bf16 v[28:31], v[164:167], v[188:191], v[28:31]
	v_mfma_f32_16x16x32_bf16 v[28:31], v[176:179], v[192:195], v[28:31]
	v_mfma_f32_16x16x32_bf16 v[20:23], v[156:159], v[196:199], v[20:23]
	v_mfma_f32_16x16x32_bf16 v[20:23], v[160:163], v[200:203], v[20:23]
	v_mfma_f32_16x16x32_bf16 v[12:15], v[164:167], v[196:199], v[12:15]
	v_mfma_f32_16x16x32_bf16 v[12:15], v[176:179], v[200:203], v[12:15]
	v_mfma_f32_16x16x32_bf16 v[4:7], v[156:159], v[204:207], v[4:7]
	v_mfma_f32_16x16x32_bf16 v[4:7], v[160:163], v[208:211], v[4:7]
	v_mfma_f32_16x16x32_bf16 v[0:3], v[164:167], v[204:207], v[0:3]
	v_mfma_f32_16x16x32_bf16 v[0:3], v[176:179], v[208:211], v[0:3]
	s_barrier
	s_setprio 0
	s_add_i32 s31, 0, 0x18000
	s_add_i32 s44, 0, 0x1c000
	v_add_u32_e32 v152, s31, v169
	v_add_u32_e32 v175, s44, v169
	ds_read_b128 v[128:131], v152
	ds_read_b128 v[132:135], v152 offset:1024
	ds_read_b128 v[148:151], v152 offset:2048
	ds_read_b128 v[152:155], v152 offset:3072
	ds_read_b128 v[156:159], v175
	ds_read_b128 v[160:163], v175 offset:1024
	ds_read_b128 v[164:167], v175 offset:2048
	ds_read_b128 v[176:179], v175 offset:3072
	s_add_u32 s42, s42, 0x4000
	s_addc_u32 s43, s43, 0
	s_mov_b32 m0, s19
	v_lshl_add_u64 v[212:213], s[42:43], 0, v[140:141]
	ds_read_b128 v[180:183], v174 offset:32768
	ds_read_b128 v[184:187], v174 offset:33792
	ds_read_b128 v[188:191], v174 offset:34816
	ds_read_b128 v[192:195], v174 offset:35840
	ds_read_b128 v[196:199], v174 offset:36864
	ds_read_b128 v[200:203], v174 offset:37888
	ds_read_b128 v[204:207], v174 offset:38912
	ds_read_b128 v[208:211], v174 offset:39936
	global_load_lds_dwordx4 v[212:213], off
	v_lshl_add_u64 v[212:213], s[42:43], 0, v[138:139]
	s_mov_b32 m0, s20
	s_nop 0
	global_load_lds_dwordx4 v[212:213], off
	s_setprio 1
	s_waitcnt vmcnt(8) lgkmcnt(0)
	s_barrier
	v_mfma_f32_16x16x32_bf16 v[124:127], v[128:131], v[180:183], v[124:127]
	v_mfma_f32_16x16x32_bf16 v[124:127], v[132:135], v[184:187], v[124:127]
	v_mfma_f32_16x16x32_bf16 v[120:123], v[148:151], v[180:183], v[120:123]
	v_mfma_f32_16x16x32_bf16 v[120:123], v[152:155], v[184:187], v[120:123]
	v_mfma_f32_16x16x32_bf16 v[108:111], v[128:131], v[188:191], v[108:111]
	v_mfma_f32_16x16x32_bf16 v[108:111], v[132:135], v[192:195], v[108:111]
	v_mfma_f32_16x16x32_bf16 v[104:107], v[148:151], v[188:191], v[104:107]
	v_mfma_f32_16x16x32_bf16 v[104:107], v[152:155], v[192:195], v[104:107]
	v_mfma_f32_16x16x32_bf16 v[92:95], v[128:131], v[196:199], v[92:95]
	v_mfma_f32_16x16x32_bf16 v[92:95], v[132:135], v[200:203], v[92:95]
	v_mfma_f32_16x16x32_bf16 v[88:91], v[148:151], v[196:199], v[88:91]
	v_mfma_f32_16x16x32_bf16 v[88:91], v[152:155], v[200:203], v[88:91]
	v_mfma_f32_16x16x32_bf16 v[76:79], v[128:131], v[204:207], v[76:79]
	v_mfma_f32_16x16x32_bf16 v[76:79], v[132:135], v[208:211], v[76:79]
	v_mfma_f32_16x16x32_bf16 v[72:75], v[148:151], v[204:207], v[72:75]
	v_mfma_f32_16x16x32_bf16 v[72:75], v[152:155], v[208:211], v[72:75]
	v_mfma_f32_16x16x32_bf16 v[116:119], v[156:159], v[180:183], v[116:119]
	v_mfma_f32_16x16x32_bf16 v[116:119], v[160:163], v[184:187], v[116:119]
	v_mfma_f32_16x16x32_bf16 v[112:115], v[164:167], v[180:183], v[112:115]
	v_mfma_f32_16x16x32_bf16 v[112:115], v[176:179], v[184:187], v[112:115]
	v_mfma_f32_16x16x32_bf16 v[100:103], v[156:159], v[188:191], v[100:103]
	v_mfma_f32_16x16x32_bf16 v[100:103], v[160:163], v[192:195], v[100:103]
	v_mfma_f32_16x16x32_bf16 v[96:99], v[164:167], v[188:191], v[96:99]
	v_mfma_f32_16x16x32_bf16 v[96:99], v[176:179], v[192:195], v[96:99]
	v_mfma_f32_16x16x32_bf16 v[84:87], v[156:159], v[196:199], v[84:87]
	v_mfma_f32_16x16x32_bf16 v[84:87], v[160:163], v[200:203], v[84:87]
	v_mfma_f32_16x16x32_bf16 v[80:83], v[164:167], v[196:199], v[80:83]
	v_mfma_f32_16x16x32_bf16 v[80:83], v[176:179], v[200:203], v[80:83]
	v_mfma_f32_16x16x32_bf16 v[68:71], v[156:159], v[204:207], v[68:71]
	v_mfma_f32_16x16x32_bf16 v[68:71], v[160:163], v[208:211], v[68:71]
	v_mfma_f32_16x16x32_bf16 v[64:67], v[164:167], v[204:207], v[64:67]
	v_mfma_f32_16x16x32_bf16 v[64:67], v[176:179], v[208:211], v[64:67]
	s_barrier
; #define PG8_STAGE(bufoff, gbase, voff) do { _Pragma("unroll") for (int _i = 0; _i < 2; ++_i) \
;         __builtin_amdgcn_global_load_lds((const unsigned*)((const char*)(gbase) + (voff)[_i]), (PG8_LAS unsigned*)(lds + (bufoff) + ldsw + _i * 8192), 16, 0, 0); } while (0)
; #define PG8_LDA(dst, b, h) do { _Pragma("unroll") for (int m = 0; m < 4; ++m) _Pragma("unroll") for (int k = 0; k < 2; ++k) dst[m][k] = *(const PG8_LAS bf16x8*)(lds + PG8_SA(b, h) + aoff + m * 2048 + k * 1024); } while (0)
; #define PG8_MMA(ai, bj, At, Bt) do { __builtin_amdgcn_s_setprio(1); _Pragma("unroll") for (int m = 0; m < 4; ++m) _Pragma("unroll") for (int n = 0; n < 2; ++n) _Pragma("unroll") for (int k = 0; k < 2; ++k) \
;         acc[ai][bj][m][n] = __builtin_amdgcn_mfma_f32_16x16x32_bf16(Bt[n][k], At[m][k], acc[ai][bj][m][n], 0, 0, 0); __builtin_amdgcn_s_setprio(0); } while (0)
; #define PG8_WAIT_V(n) asm volatile("s_waitcnt vmcnt(" #n ")" ::: "memory")
; #define PG8_WAIT_L(n) asm volatile("s_waitcnt lgkmcnt(" #n ")" ::: "memory")
; #define PG8_BAR __builtin_amdgcn_s_barrier()
; #define PG8_SCHED __builtin_amdgcn_sched_barrier(0)
; template <class Epi, class Sched, bool ALIGN_EPI = false, bool SP2 = false>
; __device__ __forceinline__ void gemm_phase(PG8_LAS unsigned char* lds, const Gemm g, const Sched& S, const Epi& E) {
;     ...
;             PG8_LDA(At, 1, 1); PG8_STAGE(PG8_SB(1, 0), b3, voffB); PG8_STAGE(PG8_SB(1, 1), b3 + hstepB, voffB); PG8_STAGE(PG8_SA(1, 0), a3, voffA);
;             PG8_WAIT_V(8); PG8_WAIT_L(0); PG8_BAR; PG8_MMA(1, 0, At, B0); PG8_MMA(1, 1, At, B1); PG8_BAR; PG8_SCHED;
;     ...
;         if constexpr (ALIGN_EPI) { if (wr == 0) PG8_BAR; }
	s_setprio 0
	s_add_u32 s42, s40, 0x8000
	s_addc_u32 s43, s41, 0
	s_add_i32 s31, s31, s14
	v_lshl_add_u64 v[212:213], s[42:43], 0, v[220:221]
	s_mov_b32 m0, s31
	ds_read_b128 v[180:183], v174 offset:49152
	ds_read_b128 v[184:187], v174 offset:50176
	ds_read_b128 v[188:191], v174 offset:51200
	ds_read_b128 v[192:195], v174 offset:52224
	ds_read_b128 v[196:199], v174 offset:53248
	ds_read_b128 v[200:203], v174 offset:54272
	ds_read_b128 v[204:207], v174 offset:55296
	ds_read_b128 v[208:211], v174 offset:56320
	global_load_lds_dwordx4 v[212:213], off
	s_add_i32 m0, s31, 0x2000
	s_add_u32 s40, s40, 0xc000
	v_lshl_add_u64 v[212:213], s[42:43], 0, v[136:137]
	s_addc_u32 s41, s41, 0
	s_add_i32 s31, s44, s14
	global_load_lds_dwordx4 v[212:213], off
	v_lshl_add_u64 v[212:213], s[40:41], 0, v[220:221]
	s_mov_b32 m0, s31
	s_nop 0
	global_load_lds_dwordx4 v[212:213], off
	v_lshl_add_u64 v[212:213], s[40:41], 0, v[136:137]
	s_add_i32 m0, s31, 0x2000
	s_nop 0
	global_load_lds_dwordx4 v[212:213], off
	v_lshl_add_u64 v[212:213], s[38:39], 0, v[140:141]
	s_mov_b32 m0, s21
	s_nop 0
	global_load_lds_dwordx4 v[212:213], off
	v_lshl_add_u64 v[212:213], s[38:39], 0, v[138:139]
	s_mov_b32 m0, s22
	s_nop 0
	global_load_lds_dwordx4 v[212:213], off
	s_setprio 1
	s_waitcnt vmcnt(8) lgkmcnt(0)
	s_barrier
	v_mfma_f32_16x16x32_bf16 v[60:63], v[128:131], v[180:183], v[60:63]
	v_mfma_f32_16x16x32_bf16 v[60:63], v[132:135], v[184:187], v[60:63]
	v_mfma_f32_16x16x32_bf16 v[56:59], v[148:151], v[180:183], v[56:59]
	v_mfma_f32_16x16x32_bf16 v[56:59], v[152:155], v[184:187], v[56:59]
	v_mfma_f32_16x16x32_bf16 v[48:51], v[128:131], v[188:191], v[48:51]
	v_mfma_f32_16x16x32_bf16 v[48:51], v[132:135], v[192:195], v[48:51]
	v_mfma_f32_16x16x32_bf16 v[40:43], v[148:151], v[188:191], v[40:43]
	v_mfma_f32_16x16x32_bf16 v[40:43], v[152:155], v[192:195], v[40:43]
	v_mfma_f32_16x16x32_bf16 v[32:35], v[128:131], v[196:199], v[32:35]
	v_mfma_f32_16x16x32_bf16 v[32:35], v[132:135], v[200:203], v[32:35]
	v_mfma_f32_16x16x32_bf16 v[24:27], v[148:151], v[196:199], v[24:27]
	v_mfma_f32_16x16x32_bf16 v[24:27], v[152:155], v[200:203], v[24:27]
	v_mfma_f32_16x16x32_bf16 v[16:19], v[128:131], v[204:207], v[16:19]
	v_mfma_f32_16x16x32_bf16 v[16:19], v[132:135], v[208:211], v[16:19]
	v_mfma_f32_16x16x32_bf16 v[8:11], v[148:151], v[204:207], v[8:11]
	v_mfma_f32_16x16x32_bf16 v[8:11], v[152:155], v[208:211], v[8:11]
	v_mfma_f32_16x16x32_bf16 v[52:55], v[156:159], v[180:183], v[52:55]
	v_mfma_f32_16x16x32_bf16 v[52:55], v[160:163], v[184:187], v[52:55]
	v_mfma_f32_16x16x32_bf16 v[44:47], v[164:167], v[180:183], v[44:47]
	v_mfma_f32_16x16x32_bf16 v[44:47], v[176:179], v[184:187], v[44:47]
	v_mfma_f32_16x16x32_bf16 v[36:39], v[156:159], v[188:191], v[36:39]
	v_mfma_f32_16x16x32_bf16 v[36:39], v[160:163], v[192:195], v[36:39]
	v_mfma_f32_16x16x32_bf16 v[28:31], v[164:167], v[188:191], v[28:31]
	v_mfma_f32_16x16x32_bf16 v[28:31], v[176:179], v[192:195], v[28:31]
	v_mfma_f32_16x16x32_bf16 v[20:23], v[156:159], v[196:199], v[20:23]
	v_mfma_f32_16x16x32_bf16 v[20:23], v[160:163], v[200:203], v[20:23]
	v_mfma_f32_16x16x32_bf16 v[12:15], v[164:167], v[196:199], v[12:15]
	v_mfma_f32_16x16x32_bf16 v[12:15], v[176:179], v[200:203], v[12:15]
	v_mfma_f32_16x16x32_bf16 v[4:7], v[156:159], v[204:207], v[4:7]
	v_mfma_f32_16x16x32_bf16 v[4:7], v[160:163], v[208:211], v[4:7]
	v_mfma_f32_16x16x32_bf16 v[0:3], v[164:167], v[204:207], v[0:3]
	v_mfma_f32_16x16x32_bf16 v[0:3], v[176:179], v[208:211], v[0:3]
	s_barrier
	s_setprio 0
	s_add_i32 s30, s30, 2
	s_add_u32 s36, s36, 0x10000
	s_addc_u32 s37, s37, 0
	s_add_u32 s28, s28, 0x10000
	s_addc_u32 s29, s29, 0
	s_cmp_gt_u32 s30, 29
	s_cbranch_scc0 .LBB0_232
	s_and_b64 vcc, exec, s[8:9]
	s_cbranch_vccz .LBB0_235
	s_barrier

; #define PG8_STAGE(bufoff, gbase, voff) do { _Pragma("unroll") for (int _i = 0; _i < 2; ++_i) \
;         __builtin_amdgcn_global_load_lds((const unsigned*)((const char*)(gbase) + (voff)[_i]), (PG8_LAS unsigned*)(lds + (bufoff) + ldsw + _i * 8192), 16, 0, 0); } while (0)
; #define PG8_LDA(dst, b, h) do { _Pragma("unroll") for (int m = 0; m < 4; ++m) _Pragma("unroll") for (int k = 0; k < 2; ++k) dst[m][k] = *(const PG8_LAS bf16x8*)(lds + PG8_SA(b, h) + aoff + m * 2048 + k * 1024); } while (0)
; #define PG8_LDB(dst, b, h) do { _Pragma("unroll") for (int n = 0; n < 2; ++n) _Pragma("unroll") for (int k = 0; k < 2; ++k) dst[n][k] = *(const PG8_LAS bf16x8*)(lds + PG8_SB(b, h) + boff + n * 2048 + k * 1024); } while (0)
; #define PG8_MMA(ai, bj, At, Bt) do { __builtin_amdgcn_s_setprio(1); _Pragma("unroll") for (int m = 0; m < 4; ++m) _Pragma("unroll") for (int n = 0; n < 2; ++n) _Pragma("unroll") for (int k = 0; k < 2; ++k) \
;         acc[ai][bj][m][n] = __builtin_amdgcn_mfma_f32_16x16x32_bf16(Bt[n][k], At[m][k], acc[ai][bj][m][n], 0, 0, 0); __builtin_amdgcn_s_setprio(0); } while (0)
; #define PG8_WAIT_V(n) asm volatile("s_waitcnt vmcnt(" #n ")" ::: "memory")
; #define PG8_WAIT_L(n) asm volatile("s_waitcnt lgkmcnt(" #n ")" ::: "memory")
; template <class Epi, class Sched, bool ALIGN_EPI = false, bool SP2 = false>
; __device__ __forceinline__ void gemm_phase(PG8_LAS unsigned char* lds, const Gemm g, const Sched& S, const Epi& E) {
;     ...
;             const bool last = (t == nt - 2);
;             const char* a1 = cA + (size_t)(t + 1) * kstepB;
;             const char* a2 = last ? nA : cA + (size_t)(t + 2) * kstepB; const char* b2 = last ? nB : cB + (size_t)(t + 2) * kstepB;
;             const char* a3 = a2 + kstepB; const char* b3 = b2 + kstepB;
;             if (last && has_next) S.a_ready(nxt);
;             if constexpr (SP2) {
;             PG8_LDB(B0, 0, 0); PG8_LDB(B1, 0, 1); PG8_SCHED; PG8_LDA(At, 0, 0); PG8_STAGE(PG8_SA(1, 1), a1 + hstepB, voffA);
;             PG8_WAIT_V(8); PG8_WAIT_L(0); PG8_BAR; PG8_MMA(0, 0, At, B0); PG8_MMA(0, 1, At, B1); PG8_BAR; PG8_SCHED;
;             PG8_LDA(At, 0, 1); PG8_STAGE(PG8_SB(0, 0), b2, voffB); PG8_STAGE(PG8_SB(0, 1), b2 + hstepB, voffB); PG8_STAGE(PG8_SA(0, 0), a2, voffA);
;             PG8_WAIT_V(8); PG8_WAIT_L(0); PG8_BAR; PG8_MMA(1, 0, At, B0); PG8_MMA(1, 1, At, B1); PG8_BAR; PG8_SCHED;
.LBB0_263:
	s_add_u32 s38, s36, 0x4000
	s_addc_u32 s39, s37, 0
	s_cmp_eq_u32 s62, 28
	s_cselect_b32 s42, s30, s38
	s_cselect_b32 s43, s13, s39
	s_cselect_b32 s40, s31, s44
	s_cselect_b32 s41, s11, s45
	s_add_u32 s38, s42, 0x8000
	s_addc_u32 s39, s43, 0
	s_add_i32 s63, 0, 0x10000
	v_add_u32_e32 v151, s63, v165
	s_add_i32 s75, 0, 0x14000
	ds_read_b128 v[128:131], v151
	ds_read_b128 v[132:135], v151 offset:1024
	ds_read_b128 v[152:155], v151 offset:2048
	ds_read_b128 v[156:159], v151 offset:3072
	v_add_u32_e32 v151, s75, v165
	ds_read_b128 v[160:163], v151
	ds_read_b128 v[170:173], v151 offset:1024
	ds_read_b128 v[174:177], v151 offset:2048
	ds_read_b128 v[178:181], v151 offset:3072
	v_lshl_add_u64 v[214:215], s[36:37], 0, v[146:147]
	s_add_i32 m0, s19, 0xc000
	ds_read_b128 v[182:185], v168
	ds_read_b128 v[186:189], v168 offset:1024
	ds_read_b128 v[190:193], v168 offset:2048
	ds_read_b128 v[194:197], v168 offset:3072
	ds_read_b128 v[198:201], v168 offset:4096
	ds_read_b128 v[202:205], v168 offset:5120
	ds_read_b128 v[206:209], v168 offset:6144
	ds_read_b128 v[210:213], v168 offset:7168
	global_load_lds_dwordx4 v[214:215], off
	v_lshl_add_u64 v[214:215], s[36:37], 0, v[148:149]
	s_add_i32 m0, s19, 0xe000
	s_nop 0
	global_load_lds_dwordx4 v[214:215], off
	s_setprio 1
	s_waitcnt vmcnt(8) lgkmcnt(0)
	s_barrier
	v_mfma_f32_16x16x32_bf16 v[124:127], v[128:131], v[182:185], v[124:127]
	v_mfma_f32_16x16x32_bf16 v[124:127], v[132:135], v[186:189], v[124:127]
	v_mfma_f32_16x16x32_bf16 v[116:119], v[152:155], v[182:185], v[116:119]
	v_mfma_f32_16x16x32_bf16 v[116:119], v[156:159], v[186:189], v[116:119]
	v_mfma_f32_16x16x32_bf16 v[108:111], v[128:131], v[190:193], v[108:111]
	v_mfma_f32_16x16x32_bf16 v[108:111], v[132:135], v[194:197], v[108:111]
	v_mfma_f32_16x16x32_bf16 v[100:103], v[152:155], v[190:193], v[100:103]
	v_mfma_f32_16x16x32_bf16 v[100:103], v[156:159], v[194:197], v[100:103]
	v_mfma_f32_16x16x32_bf16 v[92:95], v[128:131], v[198:201], v[92:95]
	v_mfma_f32_16x16x32_bf16 v[92:95], v[132:135], v[202:205], v[92:95]
	v_mfma_f32_16x16x32_bf16 v[84:87], v[152:155], v[198:201], v[84:87]
	v_mfma_f32_16x16x32_bf16 v[84:87], v[156:159], v[202:205], v[84:87]
	v_mfma_f32_16x16x32_bf16 v[76:79], v[128:131], v[206:209], v[76:79]
	v_mfma_f32_16x16x32_bf16 v[76:79], v[132:135], v[210:213], v[76:79]
	v_mfma_f32_16x16x32_bf16 v[68:71], v[152:155], v[206:209], v[68:71]
	v_mfma_f32_16x16x32_bf16 v[68:71], v[156:159], v[210:213], v[68:71]
	v_mfma_f32_16x16x32_bf16 v[120:123], v[160:163], v[182:185], v[120:123]
	v_mfma_f32_16x16x32_bf16 v[120:123], v[170:173], v[186:189], v[120:123]
	v_mfma_f32_16x16x32_bf16 v[112:115], v[174:177], v[182:185], v[112:115]
	v_mfma_f32_16x16x32_bf16 v[112:115], v[178:181], v[186:189], v[112:115]
	v_mfma_f32_16x16x32_bf16 v[104:107], v[160:163], v[190:193], v[104:107]
	v_mfma_f32_16x16x32_bf16 v[104:107], v[170:173], v[194:197], v[104:107]
	v_mfma_f32_16x16x32_bf16 v[96:99], v[174:177], v[190:193], v[96:99]
	v_mfma_f32_16x16x32_bf16 v[96:99], v[178:181], v[194:197], v[96:99]
	v_mfma_f32_16x16x32_bf16 v[88:91], v[160:163], v[198:201], v[88:91]
	v_mfma_f32_16x16x32_bf16 v[88:91], v[170:173], v[202:205], v[88:91]
	v_mfma_f32_16x16x32_bf16 v[80:83], v[174:177], v[198:201], v[80:83]
	v_mfma_f32_16x16x32_bf16 v[80:83], v[178:181], v[202:205], v[80:83]
	v_mfma_f32_16x16x32_bf16 v[72:75], v[160:163], v[206:209], v[72:75]
	v_mfma_f32_16x16x32_bf16 v[72:75], v[170:173], v[210:213], v[72:75]
	v_mfma_f32_16x16x32_bf16 v[64:67], v[174:177], v[206:209], v[64:67]
	v_mfma_f32_16x16x32_bf16 v[64:67], v[178:181], v[210:213], v[64:67]
	s_barrier
	s_setprio 0
	s_add_i32 s63, s63, s16
	v_lshl_add_u64 v[214:215], s[40:41], 0, v[140:141]
	s_mov_b32 m0, s63
	ds_read_b128 v[182:185], v168 offset:16384
	ds_read_b128 v[186:189], v168 offset:17408
	ds_read_b128 v[190:193], v168 offset:18432
	ds_read_b128 v[194:197], v168 offset:19456
	ds_read_b128 v[198:201], v168 offset:20480
	ds_read_b128 v[202:205], v168 offset:21504
	ds_read_b128 v[206:209], v168 offset:22528
	ds_read_b128 v[210:213], v168 offset:23552
	global_load_lds_dwordx4 v[214:215], off
	s_add_i32 m0, s63, 0x2000
	s_add_u32 s66, s40, 0x4000
	v_lshl_add_u64 v[214:215], s[40:41], 0, v[136:137]
	s_addc_u32 s67, s41, 0
	s_add_i32 s63, s75, s16
	global_load_lds_dwordx4 v[214:215], off
	v_lshl_add_u64 v[214:215], s[66:67], 0, v[140:141]
	s_mov_b32 m0, s63
	s_nop 0
	global_load_lds_dwordx4 v[214:215], off
	v_lshl_add_u64 v[214:215], s[66:67], 0, v[136:137]
	s_add_i32 m0, s63, 0x2000
	s_nop 0
	global_load_lds_dwordx4 v[214:215], off
	v_lshl_add_u64 v[214:215], s[42:43], 0, v[142:143]
	s_mov_b32 m0, s19
	s_nop 0
	global_load_lds_dwordx4 v[214:215], off
	v_lshl_add_u64 v[214:215], s[42:43], 0, v[138:139]
	s_mov_b32 m0, s20
	s_nop 0
	global_load_lds_dwordx4 v[214:215], off
	s_setprio 1
	s_waitcnt vmcnt(8) lgkmcnt(0)
	s_barrier
; #define PG8_STAGE(bufoff, gbase, voff) do { _Pragma("unroll") for (int _i = 0; _i < 2; ++_i) \
;         __builtin_amdgcn_global_load_lds((const unsigned*)((const char*)(gbase) + (voff)[_i]), (PG8_LAS unsigned*)(lds + (bufoff) + ldsw + _i * 8192), 16, 0, 0); } while (0)
; #define PG8_LDA(dst, b, h) do { _Pragma("unroll") for (int m = 0; m < 4; ++m) _Pragma("unroll") for (int k = 0; k < 2; ++k) dst[m][k] = *(const PG8_LAS bf16x8*)(lds + PG8_SA(b, h) + aoff + m * 2048 + k * 1024); } while (0)
; #define PG8_LDB(dst, b, h) do { _Pragma("unroll") for (int n = 0; n < 2; ++n) _Pragma("unroll") for (int k = 0; k < 2; ++k) dst[n][k] = *(const PG8_LAS bf16x8*)(lds + PG8_SB(b, h) + boff + n * 2048 + k * 1024); } while (0)
; #define PG8_MMA(ai, bj, At, Bt) do { __builtin_amdgcn_s_setprio(1); _Pragma("unroll") for (int m = 0; m < 4; ++m) _Pragma("unroll") for (int n = 0; n < 2; ++n) _Pragma("unroll") for (int k = 0; k < 2; ++k) \
;         acc[ai][bj][m][n] = __builtin_amdgcn_mfma_f32_16x16x32_bf16(Bt[n][k], At[m][k], acc[ai][bj][m][n], 0, 0, 0); __builtin_amdgcn_s_setprio(0); } while (0)
; #define PG8_WAIT_V(n) asm volatile("s_waitcnt vmcnt(" #n ")" ::: "memory")
; #define PG8_WAIT_L(n) asm volatile("s_waitcnt lgkmcnt(" #n ")" ::: "memory")
; #define PG8_BAR __builtin_amdgcn_s_barrier()
; #define PG8_SCHED __builtin_amdgcn_sched_barrier(0)
; template <class Epi, class Sched, bool ALIGN_EPI = false, bool SP2 = false>
; __device__ __forceinline__ void gemm_phase(PG8_LAS unsigned char* lds, const Gemm g, const Sched& S, const Epi& E) {
;     ...
;             PG8_WAIT_V(8); PG8_WAIT_L(0); PG8_BAR; PG8_MMA(1, 0, At, B0); PG8_MMA(1, 1, At, B1); PG8_BAR; PG8_SCHED;
;             PG8_LDB(B0, 1, 0); PG8_LDB(B1, 1, 1); PG8_SCHED; PG8_LDA(At, 1, 0); PG8_STAGE(PG8_SA(0, 1), a2 + hstepB, voffA);
;             PG8_WAIT_V(8); PG8_WAIT_L(0); PG8_BAR; PG8_MMA(0, 0, At, B0); PG8_MMA(0, 1, At, B1); PG8_BAR; PG8_SCHED;
	v_mfma_f32_16x16x32_bf16 v[60:63], v[128:131], v[182:185], v[60:63]
	v_mfma_f32_16x16x32_bf16 v[60:63], v[132:135], v[186:189], v[60:63]
	v_mfma_f32_16x16x32_bf16 v[52:55], v[152:155], v[182:185], v[52:55]
	v_mfma_f32_16x16x32_bf16 v[52:55], v[156:159], v[186:189], v[52:55]
	v_mfma_f32_16x16x32_bf16 v[44:47], v[128:131], v[190:193], v[44:47]
	v_mfma_f32_16x16x32_bf16 v[44:47], v[132:135], v[194:197], v[44:47]
	v_mfma_f32_16x16x32_bf16 v[36:39], v[152:155], v[190:193], v[36:39]
	v_mfma_f32_16x16x32_bf16 v[36:39], v[156:159], v[194:197], v[36:39]
	v_mfma_f32_16x16x32_bf16 v[28:31], v[128:131], v[198:201], v[28:31]
	v_mfma_f32_16x16x32_bf16 v[28:31], v[132:135], v[202:205], v[28:31]
	v_mfma_f32_16x16x32_bf16 v[20:23], v[152:155], v[198:201], v[20:23]
	v_mfma_f32_16x16x32_bf16 v[20:23], v[156:159], v[202:205], v[20:23]
	v_mfma_f32_16x16x32_bf16 v[12:15], v[128:131], v[206:209], v[12:15]
	v_mfma_f32_16x16x32_bf16 v[12:15], v[132:135], v[210:213], v[12:15]
	v_mfma_f32_16x16x32_bf16 v[4:7], v[152:155], v[206:209], v[4:7]
	v_mfma_f32_16x16x32_bf16 v[4:7], v[156:159], v[210:213], v[4:7]
	v_mfma_f32_16x16x32_bf16 v[56:59], v[160:163], v[182:185], v[56:59]
	v_mfma_f32_16x16x32_bf16 v[56:59], v[170:173], v[186:189], v[56:59]
	v_mfma_f32_16x16x32_bf16 v[48:51], v[174:177], v[182:185], v[48:51]
	v_mfma_f32_16x16x32_bf16 v[48:51], v[178:181], v[186:189], v[48:51]
	v_mfma_f32_16x16x32_bf16 v[40:43], v[160:163], v[190:193], v[40:43]
	v_mfma_f32_16x16x32_bf16 v[40:43], v[170:173], v[194:197], v[40:43]
	v_mfma_f32_16x16x32_bf16 v[32:35], v[174:177], v[190:193], v[32:35]
	v_mfma_f32_16x16x32_bf16 v[32:35], v[178:181], v[194:197], v[32:35]
	v_mfma_f32_16x16x32_bf16 v[24:27], v[160:163], v[198:201], v[24:27]
	v_mfma_f32_16x16x32_bf16 v[24:27], v[170:173], v[202:205], v[24:27]
	v_mfma_f32_16x16x32_bf16 v[16:19], v[174:177], v[198:201], v[16:19]
	v_mfma_f32_16x16x32_bf16 v[16:19], v[178:181], v[202:205], v[16:19]
	v_mfma_f32_16x16x32_bf16 v[8:11], v[160:163], v[206:209], v[8:11]
	v_mfma_f32_16x16x32_bf16 v[8:11], v[170:173], v[210:213], v[8:11]
	v_mfma_f32_16x16x32_bf16 v[0:3], v[174:177], v[206:209], v[0:3]
	v_mfma_f32_16x16x32_bf16 v[0:3], v[178:181], v[210:213], v[0:3]
	s_barrier
	s_setprio 0
	s_add_i32 s63, 0, 0x18000
	v_add_u32_e32 v151, s63, v165
	s_add_i32 s66, 0, 0x1c000
	ds_read_b128 v[128:131], v151
	ds_read_b128 v[132:135], v151 offset:1024
	ds_read_b128 v[152:155], v151 offset:2048
	ds_read_b128 v[156:159], v151 offset:3072
	v_add_u32_e32 v151, s66, v165
	ds_read_b128 v[160:163], v151
	ds_read_b128 v[170:173], v151 offset:1024
	ds_read_b128 v[174:177], v151 offset:2048
	ds_read_b128 v[178:181], v151 offset:3072
	s_add_u32 s42, s42, 0x4000
	s_addc_u32 s43, s43, 0
	s_mov_b32 m0, s21
	v_lshl_add_u64 v[214:215], s[42:43], 0, v[142:143]
	ds_read_b128 v[182:185], v168 offset:32768
	ds_read_b128 v[186:189], v168 offset:33792
	ds_read_b128 v[190:193], v168 offset:34816
	ds_read_b128 v[194:197], v168 offset:35840
	ds_read_b128 v[198:201], v168 offset:36864
	ds_read_b128 v[202:205], v168 offset:37888
	ds_read_b128 v[206:209], v168 offset:38912
	ds_read_b128 v[210:213], v168 offset:39936
	global_load_lds_dwordx4 v[214:215], off
	v_lshl_add_u64 v[214:215], s[42:43], 0, v[138:139]
	s_mov_b32 m0, s22
	s_nop 0
	global_load_lds_dwordx4 v[214:215], off
	s_setprio 1
	s_waitcnt vmcnt(8) lgkmcnt(0)
	s_barrier
	v_mfma_f32_16x16x32_bf16 v[124:127], v[128:131], v[182:185], v[124:127]
	v_mfma_f32_16x16x32_bf16 v[124:127], v[132:135], v[186:189], v[124:127]
	v_mfma_f32_16x16x32_bf16 v[116:119], v[152:155], v[182:185], v[116:119]
	v_mfma_f32_16x16x32_bf16 v[116:119], v[156:159], v[186:189], v[116:119]
	v_mfma_f32_16x16x32_bf16 v[108:111], v[128:131], v[190:193], v[108:111]
	v_mfma_f32_16x16x32_bf16 v[108:111], v[132:135], v[194:197], v[108:111]
	v_mfma_f32_16x16x32_bf16 v[100:103], v[152:155], v[190:193], v[100:103]
	v_mfma_f32_16x16x32_bf16 v[100:103], v[156:159], v[194:197], v[100:103]
	v_mfma_f32_16x16x32_bf16 v[92:95], v[128:131], v[198:201], v[92:95]
	v_mfma_f32_16x16x32_bf16 v[92:95], v[132:135], v[202:205], v[92:95]
	v_mfma_f32_16x16x32_bf16 v[84:87], v[152:155], v[198:201], v[84:87]
	v_mfma_f32_16x16x32_bf16 v[84:87], v[156:159], v[202:205], v[84:87]
	v_mfma_f32_16x16x32_bf16 v[76:79], v[128:131], v[206:209], v[76:79]
	v_mfma_f32_16x16x32_bf16 v[76:79], v[132:135], v[210:213], v[76:79]
	v_mfma_f32_16x16x32_bf16 v[68:71], v[152:155], v[206:209], v[68:71]
	v_mfma_f32_16x16x32_bf16 v[68:71], v[156:159], v[210:213], v[68:71]
	v_mfma_f32_16x16x32_bf16 v[120:123], v[160:163], v[182:185], v[120:123]
	v_mfma_f32_16x16x32_bf16 v[120:123], v[170:173], v[186:189], v[120:123]
	v_mfma_f32_16x16x32_bf16 v[112:115], v[174:177], v[182:185], v[112:115]
	v_mfma_f32_16x16x32_bf16 v[112:115], v[178:181], v[186:189], v[112:115]
	v_mfma_f32_16x16x32_bf16 v[104:107], v[160:163], v[190:193], v[104:107]
	v_mfma_f32_16x16x32_bf16 v[104:107], v[170:173], v[194:197], v[104:107]
	v_mfma_f32_16x16x32_bf16 v[96:99], v[174:177], v[190:193], v[96:99]
	v_mfma_f32_16x16x32_bf16 v[96:99], v[178:181], v[194:197], v[96:99]
	v_mfma_f32_16x16x32_bf16 v[88:91], v[160:163], v[198:201], v[88:91]
	v_mfma_f32_16x16x32_bf16 v[88:91], v[170:173], v[202:205], v[88:91]
	v_mfma_f32_16x16x32_bf16 v[80:83], v[174:177], v[198:201], v[80:83]
	v_mfma_f32_16x16x32_bf16 v[80:83], v[178:181], v[202:205], v[80:83]
	v_mfma_f32_16x16x32_bf16 v[72:75], v[160:163], v[206:209], v[72:75]
	v_mfma_f32_16x16x32_bf16 v[72:75], v[170:173], v[210:213], v[72:75]
	v_mfma_f32_16x16x32_bf16 v[64:67], v[174:177], v[206:209], v[64:67]
	v_mfma_f32_16x16x32_bf16 v[64:67], v[178:181], v[210:213], v[64:67]
	s_barrier
; #define PG8_STAGE(bufoff, gbase, voff) do { _Pragma("unroll") for (int _i = 0; _i < 2; ++_i) \
;         __builtin_amdgcn_global_load_lds((const unsigned*)((const char*)(gbase) + (voff)[_i]), (PG8_LAS unsigned*)(lds + (bufoff) + ldsw + _i * 8192), 16, 0, 0); } while (0)
; #define PG8_LDA(dst, b, h) do { _Pragma("unroll") for (int m = 0; m < 4; ++m) _Pragma("unroll") for (int k = 0; k < 2; ++k) dst[m][k] = *(const PG8_LAS bf16x8*)(lds + PG8_SA(b, h) + aoff + m * 2048 + k * 1024); } while (0)
; #define PG8_MMA(ai, bj, At, Bt) do { __builtin_amdgcn_s_setprio(1); _Pragma("unroll") for (int m = 0; m < 4; ++m) _Pragma("unroll") for (int n = 0; n < 2; ++n) _Pragma("unroll") for (int k = 0; k < 2; ++k) \
;         acc[ai][bj][m][n] = __builtin_amdgcn_mfma_f32_16x16x32_bf16(Bt[n][k], At[m][k], acc[ai][bj][m][n], 0, 0, 0); __builtin_amdgcn_s_setprio(0); } while (0)
; #define PG8_WAIT_V(n) asm volatile("s_waitcnt vmcnt(" #n ")" ::: "memory")
; #define PG8_WAIT_L(n) asm volatile("s_waitcnt lgkmcnt(" #n ")" ::: "memory")
; #define PG8_BAR __builtin_amdgcn_s_barrier()
; #define PG8_SCHED __builtin_amdgcn_sched_barrier(0)
; template <class Epi, class Sched, bool ALIGN_EPI = false, bool SP2 = false>
; __device__ __forceinline__ void gemm_phase(PG8_LAS unsigned char* lds, const Gemm g, const Sched& S, const Epi& E) {
;     ...
;             PG8_LDA(At, 1, 1); PG8_STAGE(PG8_SB(1, 0), b3, voffB); PG8_STAGE(PG8_SB(1, 1), b3 + hstepB, voffB); PG8_STAGE(PG8_SA(1, 0), a3, voffA);
;             PG8_WAIT_V(8); PG8_WAIT_L(0); PG8_BAR; PG8_MMA(1, 0, At, B0); PG8_MMA(1, 1, At, B1); PG8_BAR; PG8_SCHED;
;     ...
;         if constexpr (ALIGN_EPI) { if (wr == 0) PG8_BAR; }
	s_setprio 0
	s_add_u32 s42, s40, 0x8000
	s_addc_u32 s43, s41, 0
	s_add_i32 s63, s63, s16
	v_lshl_add_u64 v[214:215], s[42:43], 0, v[140:141]
	s_mov_b32 m0, s63
	ds_read_b128 v[182:185], v168 offset:49152
	ds_read_b128 v[186:189], v168 offset:50176
	ds_read_b128 v[190:193], v168 offset:51200
	ds_read_b128 v[194:197], v168 offset:52224
	ds_read_b128 v[198:201], v168 offset:53248
	ds_read_b128 v[202:205], v168 offset:54272
	ds_read_b128 v[206:209], v168 offset:55296
	ds_read_b128 v[210:213], v168 offset:56320
	global_load_lds_dwordx4 v[214:215], off
	s_add_i32 m0, s63, 0x2000
	s_add_u32 s40, s40, 0xc000
	v_lshl_add_u64 v[214:215], s[42:43], 0, v[136:137]
	s_addc_u32 s41, s41, 0
	s_add_i32 s42, s66, s16
	global_load_lds_dwordx4 v[214:215], off
	v_lshl_add_u64 v[214:215], s[40:41], 0, v[140:141]
	s_mov_b32 m0, s42
	s_nop 0
	global_load_lds_dwordx4 v[214:215], off
	v_lshl_add_u64 v[214:215], s[40:41], 0, v[136:137]
	s_add_i32 m0, s42, 0x2000
	s_nop 0
	global_load_lds_dwordx4 v[214:215], off
	v_lshl_add_u64 v[214:215], s[38:39], 0, v[142:143]
	s_mov_b32 m0, s25
	s_nop 0
	global_load_lds_dwordx4 v[214:215], off
	v_lshl_add_u64 v[214:215], s[38:39], 0, v[138:139]
	s_mov_b32 m0, s26
	s_nop 0
	global_load_lds_dwordx4 v[214:215], off
	s_setprio 1
	s_waitcnt vmcnt(8) lgkmcnt(0)
	s_barrier
	v_mfma_f32_16x16x32_bf16 v[60:63], v[128:131], v[182:185], v[60:63]
	v_mfma_f32_16x16x32_bf16 v[60:63], v[132:135], v[186:189], v[60:63]
	v_mfma_f32_16x16x32_bf16 v[52:55], v[152:155], v[182:185], v[52:55]
	v_mfma_f32_16x16x32_bf16 v[52:55], v[156:159], v[186:189], v[52:55]
	v_mfma_f32_16x16x32_bf16 v[44:47], v[128:131], v[190:193], v[44:47]
	v_mfma_f32_16x16x32_bf16 v[44:47], v[132:135], v[194:197], v[44:47]
	v_mfma_f32_16x16x32_bf16 v[36:39], v[152:155], v[190:193], v[36:39]
	v_mfma_f32_16x16x32_bf16 v[36:39], v[156:159], v[194:197], v[36:39]
	v_mfma_f32_16x16x32_bf16 v[28:31], v[128:131], v[198:201], v[28:31]
	v_mfma_f32_16x16x32_bf16 v[28:31], v[132:135], v[202:205], v[28:31]
	v_mfma_f32_16x16x32_bf16 v[20:23], v[152:155], v[198:201], v[20:23]
	v_mfma_f32_16x16x32_bf16 v[20:23], v[156:159], v[202:205], v[20:23]
	v_mfma_f32_16x16x32_bf16 v[12:15], v[128:131], v[206:209], v[12:15]
	v_mfma_f32_16x16x32_bf16 v[12:15], v[132:135], v[210:213], v[12:15]
	v_mfma_f32_16x16x32_bf16 v[4:7], v[152:155], v[206:209], v[4:7]
	v_mfma_f32_16x16x32_bf16 v[4:7], v[156:159], v[210:213], v[4:7]
	v_mfma_f32_16x16x32_bf16 v[56:59], v[160:163], v[182:185], v[56:59]
	v_mfma_f32_16x16x32_bf16 v[56:59], v[170:173], v[186:189], v[56:59]
	v_mfma_f32_16x16x32_bf16 v[48:51], v[174:177], v[182:185], v[48:51]
	v_mfma_f32_16x16x32_bf16 v[48:51], v[178:181], v[186:189], v[48:51]
	v_mfma_f32_16x16x32_bf16 v[40:43], v[160:163], v[190:193], v[40:43]
	v_mfma_f32_16x16x32_bf16 v[40:43], v[170:173], v[194:197], v[40:43]
	v_mfma_f32_16x16x32_bf16 v[32:35], v[174:177], v[190:193], v[32:35]
	v_mfma_f32_16x16x32_bf16 v[32:35], v[178:181], v[194:197], v[32:35]
	v_mfma_f32_16x16x32_bf16 v[24:27], v[160:163], v[198:201], v[24:27]
	v_mfma_f32_16x16x32_bf16 v[24:27], v[170:173], v[202:205], v[24:27]
	v_mfma_f32_16x16x32_bf16 v[16:19], v[174:177], v[198:201], v[16:19]
	v_mfma_f32_16x16x32_bf16 v[16:19], v[178:181], v[202:205], v[16:19]
	v_mfma_f32_16x16x32_bf16 v[8:11], v[160:163], v[206:209], v[8:11]
	v_mfma_f32_16x16x32_bf16 v[8:11], v[170:173], v[210:213], v[8:11]
	v_mfma_f32_16x16x32_bf16 v[0:3], v[174:177], v[206:209], v[0:3]
	v_mfma_f32_16x16x32_bf16 v[0:3], v[178:181], v[210:213], v[0:3]
	s_barrier
	s_setprio 0
	s_add_i32 s62, s62, 2
	s_add_u32 s36, s36, 0x10000
	s_addc_u32 s37, s37, 0
	s_add_u32 s44, s44, 0x10000
	s_addc_u32 s45, s45, 0
	s_cmp_gt_u32 s62, 29
	s_cbranch_scc0 .LBB0_263
	s_and_b64 vcc, exec, s[8:9]
	s_cbranch_vccz .LBB0_266
	s_barrier
